# mLSTM-prep DN loop: the eight 16-bit LDS reads of each block are issued together with one wait instead of a wait after every read
# speedup vs baseline: 1.0294x; 1.0145x over previous
.LBB0_635:
	v_add_u32_e32 v3, s1, v166
	ds_read_b128 v[76:79], v3
	ds_read_b128 v[80:83], v3 offset:16
	ds_read_u16 v84, v2
	ds_read_u16 v85, v2 offset:208
	ds_read_u16 v86, v2 offset:416
	ds_read_u16 v87, v2 offset:624
	ds_read_u16 v88, v2 offset:832
	ds_read_u16 v89, v2 offset:1040
	ds_read_u16 v90, v2 offset:1248
	ds_read_u16 v91, v2 offset:1456
	s_add_i32 s1, s1, 32
	v_add_u32_e32 v2, 0x680, v2
	s_waitcnt lgkmcnt(0)
	v_lshlrev_b32_e32 v84, 16, v84
	v_fmac_f32_e32 v0, v76, v84
	v_lshlrev_b32_e32 v85, 16, v85
	v_fmac_f32_e32 v0, v77, v85
	v_lshlrev_b32_e32 v86, 16, v86
	v_fmac_f32_e32 v0, v78, v86
	v_lshlrev_b32_e32 v87, 16, v87
	v_fmac_f32_e32 v0, v79, v87
	v_lshlrev_b32_e32 v88, 16, v88
	v_fmac_f32_e32 v0, v80, v88
	v_lshlrev_b32_e32 v89, 16, v89
	v_fmac_f32_e32 v0, v81, v89
	v_lshlrev_b32_e32 v90, 16, v90
	v_fmac_f32_e32 v0, v82, v90
	v_lshlrev_b32_e32 v91, 16, v91
	v_fmac_f32_e32 v0, v83, v91
	s_cmpk_eq_i32 s1, 0x100
	s_cbranch_scc0 .LBB0_635
	v_or_b32_e32 v2, s76, v170
	v_ashrrev_i32_e32 v3, 31, v2
	v_lshlrev_b64 v[2:3], 2, v[2:3]
	v_or_b32_e32 v2, v2, v116
	s_movk_i32 s1, 0x180
	v_mad_u64_u32 v[76:77], s[80:81], v2, s1, v[106:107]
	v_mad_i32_i24 v77, v3, s1, v77
	global_store_dword v[76:77], v0, off
